# v67 + removal of three dead VALU ops per banded tile (both modes)
# baseline (speedup 1.0000x reference)
.Lpf_nq:
	v_add_u32_e32 v0, s9, v212
	v_cvt_f32_i32_e32 v32, v0
	s_and_b64 vcc, exec, s[10:11]
	s_cbranch_vccnz .LBB0_906
	v_add_f32_e32 v1, 1.0, v32
	v_cmp_le_f32_e64 vcc, |v32|, s92
	v_cmp_le_f32_e64 s[10:11], |v1|, s92
	v_fma_f32 v0, s38, -|v32|, v66
	v_fma_f32 v1, s38, -|v1|, v67
	v_cndmask_b32_e32 v0, v242, v0, vcc
	v_cndmask_b32_e64 v1, v242, v1, s[10:11]
	v_add_f32_e32 v2, 2.0, v32
	v_add_f32_e32 v3, 0x40400000, v32
	v_cmp_le_f32_e64 vcc, |v2|, s92
	v_cmp_le_f32_e64 s[10:11], |v3|, s92
	v_fma_f32 v2, s38, -|v2|, v68
	v_fma_f32 v3, s38, -|v3|, v69
	v_cndmask_b32_e32 v2, v242, v2, vcc
	v_cndmask_b32_e64 v3, v242, v3, s[10:11]
	v_add_f32_e32 v4, 0x41000000, v32
	v_add_f32_e32 v5, 0x41100000, v32
	v_cmp_le_f32_e64 vcc, |v4|, s92
	v_cmp_le_f32_e64 s[10:11], |v5|, s92
	v_fma_f32 v4, s38, -|v4|, v70
	v_fma_f32 v5, s38, -|v5|, v71
	v_cndmask_b32_e32 v4, v242, v4, vcc
	v_cndmask_b32_e64 v5, v242, v5, s[10:11]
	v_add_f32_e32 v6, 0x41200000, v32
	v_add_f32_e32 v7, 0x41300000, v32
	v_cmp_le_f32_e64 vcc, |v6|, s92
	v_cmp_le_f32_e64 s[10:11], |v7|, s92
	v_fma_f32 v6, s38, -|v6|, v72
	v_fma_f32 v7, s38, -|v7|, v73
	v_cndmask_b32_e32 v6, v242, v6, vcc
	v_cndmask_b32_e64 v7, v242, v7, s[10:11]
	v_add_f32_e32 v8, 0x41800000, v32
	v_add_f32_e32 v9, 0x41880000, v32
	v_cmp_le_f32_e64 vcc, |v8|, s92
	v_cmp_le_f32_e64 s[10:11], |v9|, s92
	v_fma_f32 v8, s38, -|v8|, v74
	v_fma_f32 v9, s38, -|v9|, v75
	v_cndmask_b32_e32 v8, v242, v8, vcc
	v_cndmask_b32_e64 v9, v242, v9, s[10:11]
	v_add_f32_e32 v10, 0x41900000, v32
	v_add_f32_e32 v11, 0x41980000, v32
	v_cmp_le_f32_e64 vcc, |v10|, s92
	v_cmp_le_f32_e64 s[10:11], |v11|, s92
	v_fma_f32 v10, s38, -|v10|, v76
	v_fma_f32 v11, s38, -|v11|, v77
	v_cndmask_b32_e32 v10, v242, v10, vcc
	v_cndmask_b32_e64 v11, v242, v11, s[10:11]
	v_add_f32_e32 v12, 0x41c00000, v32
	v_add_f32_e32 v13, 0x41c80000, v32
	v_cmp_le_f32_e64 vcc, |v12|, s92
	v_cmp_le_f32_e64 s[10:11], |v13|, s92
	v_fma_f32 v12, s38, -|v12|, v78
	v_fma_f32 v13, s38, -|v13|, v79
	v_cndmask_b32_e32 v12, v242, v12, vcc
	v_cndmask_b32_e64 v13, v242, v13, s[10:11]
	v_add_f32_e32 v14, 0x41d00000, v32
	v_add_f32_e32 v15, 0x41d80000, v32
	v_cmp_le_f32_e64 vcc, |v14|, s92
	v_cmp_le_f32_e64 s[10:11], |v15|, s92
	v_fma_f32 v14, s38, -|v14|, v80
	v_fma_f32 v15, s38, -|v15|, v81
	v_cndmask_b32_e32 v14, v242, v14, vcc
	v_cndmask_b32_e64 v15, v242, v15, s[10:11]
	v_add_f32_e32 v16, 0x42000000, v32
	v_add_f32_e32 v17, 0x42040000, v32
	v_cmp_le_f32_e64 vcc, |v16|, s92
	v_cmp_le_f32_e64 s[10:11], |v17|, s92
	v_fma_f32 v16, s38, -|v16|, v82
	v_fma_f32 v17, s38, -|v17|, v83
	v_cndmask_b32_e32 v16, v242, v16, vcc
	v_cndmask_b32_e64 v17, v242, v17, s[10:11]
	v_add_f32_e32 v18, 0x42080000, v32
	v_add_f32_e32 v19, 0x420c0000, v32
	v_cmp_le_f32_e64 vcc, |v18|, s92
	v_cmp_le_f32_e64 s[10:11], |v19|, s92
	v_fma_f32 v18, s38, -|v18|, v84
	v_fma_f32 v19, s38, -|v19|, v85
	v_cndmask_b32_e32 v18, v242, v18, vcc
	v_cndmask_b32_e64 v19, v242, v19, s[10:11]
	v_add_f32_e32 v20, 0x42200000, v32
	v_add_f32_e32 v21, 0x42240000, v32
	v_cmp_le_f32_e64 vcc, |v20|, s92
	v_cmp_le_f32_e64 s[10:11], |v21|, s92
	v_fma_f32 v20, s38, -|v20|, v86
	v_fma_f32 v21, s38, -|v21|, v87
	v_cndmask_b32_e32 v20, v242, v20, vcc
	v_cndmask_b32_e64 v21, v242, v21, s[10:11]
	v_add_f32_e32 v22, 0x42280000, v32
	v_add_f32_e32 v23, 0x422c0000, v32
	v_cmp_le_f32_e64 vcc, |v22|, s92
	v_cmp_le_f32_e64 s[10:11], |v23|, s92
	v_fma_f32 v22, s38, -|v22|, v88
	v_fma_f32 v23, s38, -|v23|, v89
	v_cndmask_b32_e32 v22, v242, v22, vcc
	v_cndmask_b32_e64 v23, v242, v23, s[10:11]
	v_add_f32_e32 v24, 0x42400000, v32
	v_add_f32_e32 v25, 0x42440000, v32
	v_cmp_le_f32_e64 vcc, |v24|, s92
	v_cmp_le_f32_e64 s[10:11], |v25|, s92
	v_fma_f32 v24, s38, -|v24|, v90
	v_fma_f32 v25, s38, -|v25|, v91
	v_cndmask_b32_e32 v24, v242, v24, vcc
	v_cndmask_b32_e64 v25, v242, v25, s[10:11]
	v_add_f32_e32 v26, 0x42480000, v32
	v_add_f32_e32 v27, 0x424c0000, v32
	v_cmp_le_f32_e64 vcc, |v26|, s92
	v_cmp_le_f32_e64 s[10:11], |v27|, s92
	v_fma_f32 v26, s38, -|v26|, v92
	v_fma_f32 v27, s38, -|v27|, v93
	v_cndmask_b32_e32 v26, v242, v26, vcc
	v_cndmask_b32_e64 v27, v242, v27, s[10:11]
	v_add_f32_e32 v28, 0x42600000, v32
	v_add_f32_e32 v29, 0x42640000, v32
	v_cmp_le_f32_e64 vcc, |v28|, s92
	v_cmp_le_f32_e64 s[10:11], |v29|, s92
	v_fma_f32 v28, s38, -|v28|, v94
	v_fma_f32 v29, s38, -|v29|, v95
	v_cndmask_b32_e32 v28, v242, v28, vcc
	v_cndmask_b32_e64 v29, v242, v29, s[10:11]
	v_add_f32_e32 v30, 0x42680000, v32
	v_add_f32_e32 v31, 0x426c0000, v32
	v_cmp_le_f32_e64 vcc, |v30|, s92
	v_cmp_le_f32_e64 s[10:11], |v31|, s92
	v_fma_f32 v30, s38, -|v30|, v96
	v_fma_f32 v31, s38, -|v31|, v97
	v_cndmask_b32_e32 v30, v242, v30, vcc
	v_cndmask_b32_e64 v31, v242, v31, s[10:11]
	s_mov_b64 s[44:45], 0

.LBB0_919:
	s_waitcnt vmcnt(0)
	v_mfma_f32_32x32x16_bf16 v[66:81], v[142:145], v[98:101], 0
	s_mov_b32 s16, s44
	s_add_i32 s44, s44, 1
	s_cmp_ge_u32 s44, s5
	v_lshl_add_u64 v[0:1], v[202:203], 0, s[48:49]
	s_cselect_b64 s[50:51], -1, 0
	s_cmp_lt_u32 s44, s5
	global_load_dwordx4 v[174:177], v[0:1], off
	global_load_dwordx4 v[170:173], v[0:1], off offset:1024
	global_load_dwordx4 v[166:169], v[0:1], off offset:2048
	global_load_dwordx4 v[162:165], v[0:1], off offset:3072
	v_mfma_f32_32x32x16_bf16 v[82:97], v[126:129], v[98:101], 0
	v_add_co_u32_e32 v0, vcc, s79, v0
	s_cselect_b32 s16, s44, s16
	s_nop 0
	v_addc_co_u32_e32 v1, vcc, 0, v1, vcc
	s_lshl_b64 s[48:49], s[16:17], 13
	global_load_dwordx4 v[158:161], v[0:1], off
	global_load_dwordx4 v[154:157], v[0:1], off offset:1024
	global_load_dwordx4 v[150:153], v[0:1], off offset:2048
	global_load_dwordx4 v[146:149], v[0:1], off offset:3072
	v_mfma_f32_32x32x16_bf16 v[66:81], v[138:141], v[102:105], v[66:81]
	v_lshl_add_u64 v[0:1], v[184:185], 0, s[48:49]
	global_load_dwordx4 v[142:145], v[0:1], off
	global_load_dwordx4 v[138:141], v[0:1], off offset:1024
	s_cmp_le_u32 s33, s4
	s_cselect_b64 s[52:53], -1, 0
	s_cmp_gt_i32 s33, s6
	v_mfma_f32_32x32x16_bf16 v[82:97], v[122:125], v[102:105], v[82:97]
	v_mfma_f32_32x32x16_bf16 v[66:81], v[134:137], v[106:109], v[66:81]
	v_mfma_f32_32x32x16_bf16 v[82:97], v[118:121], v[106:109], v[82:97]
	v_mfma_f32_32x32x16_bf16 v[66:81], v[130:133], v[110:113], v[66:81]
	global_load_dwordx4 v[134:137], v[0:1], off offset:2048
	global_load_dwordx4 v[130:133], v[0:1], off offset:3072
	v_add_co_u32_e32 v0, vcc, s79, v0
	s_nop 1
	v_addc_co_u32_e32 v1, vcc, 0, v1, vcc
	global_load_dwordx4 v[126:129], v[0:1], off
	global_load_dwordx4 v[122:125], v[0:1], off offset:1024
	v_mfma_f32_32x32x16_bf16 v[82:97], v[114:117], v[110:113], v[82:97]
	global_load_dwordx4 v[118:121], v[0:1], off offset:2048
	global_load_dwordx4 v[114:117], v[0:1], off offset:3072
	v_add_u32_e32 v0, s33, v212
	v_cvt_f32_i32_e32 v206, v0
	s_cselect_b64 vcc, -1, 0
	s_and_b64 vcc, s[52:53], vcc
	s_mov_b64 s[52:53], -1
	s_and_b64 vcc, exec, vcc
	s_cbranch_vccnz .LBB0_921
	v_add_f32_e32 v1, 1.0, v206
	v_cmp_le_f32_e64 vcc, |v206|, s91
	v_cmp_le_f32_e64 s[52:53], |v1|, s91
	v_fma_f32 v0, s46, -|v206|, v66
	v_fma_f32 v1, s46, -|v1|, v67
	v_cndmask_b32_e32 v0, v242, v0, vcc
	v_cndmask_b32_e64 v1, v242, v1, s[52:53]
	v_add_f32_e32 v2, 2.0, v206
	v_add_f32_e32 v3, 0x40400000, v206
	v_cmp_le_f32_e64 vcc, |v2|, s91
	v_cmp_le_f32_e64 s[52:53], |v3|, s91
	v_fma_f32 v2, s46, -|v2|, v68
	v_fma_f32 v3, s46, -|v3|, v69
	v_cndmask_b32_e32 v2, v242, v2, vcc
	v_cndmask_b32_e64 v3, v242, v3, s[52:53]
	v_add_f32_e32 v4, 0x41000000, v206
	v_add_f32_e32 v5, 0x41100000, v206
	v_cmp_le_f32_e64 vcc, |v4|, s91
	v_cmp_le_f32_e64 s[52:53], |v5|, s91
	v_fma_f32 v4, s46, -|v4|, v70
	v_fma_f32 v5, s46, -|v5|, v71
	v_cndmask_b32_e32 v4, v242, v4, vcc
	v_cndmask_b32_e64 v5, v242, v5, s[52:53]
	v_add_f32_e32 v6, 0x41200000, v206
	v_add_f32_e32 v7, 0x41300000, v206
	v_cmp_le_f32_e64 vcc, |v6|, s91
	v_cmp_le_f32_e64 s[52:53], |v7|, s91
	v_fma_f32 v6, s46, -|v6|, v72
	v_fma_f32 v7, s46, -|v7|, v73
	v_cndmask_b32_e32 v6, v242, v6, vcc
	v_cndmask_b32_e64 v7, v242, v7, s[52:53]
	v_add_f32_e32 v8, 0x41800000, v206
	v_add_f32_e32 v9, 0x41880000, v206
	v_cmp_le_f32_e64 vcc, |v8|, s91
	v_cmp_le_f32_e64 s[52:53], |v9|, s91
	v_fma_f32 v8, s46, -|v8|, v74
	v_fma_f32 v9, s46, -|v9|, v75
	v_cndmask_b32_e32 v8, v242, v8, vcc
	v_cndmask_b32_e64 v9, v242, v9, s[52:53]
	v_add_f32_e32 v10, 0x41900000, v206
	v_add_f32_e32 v11, 0x41980000, v206
	v_cmp_le_f32_e64 vcc, |v10|, s91
	v_cmp_le_f32_e64 s[52:53], |v11|, s91
	v_fma_f32 v10, s46, -|v10|, v76
	v_fma_f32 v11, s46, -|v11|, v77
	v_cndmask_b32_e32 v10, v242, v10, vcc
	v_cndmask_b32_e64 v11, v242, v11, s[52:53]
	v_add_f32_e32 v12, 0x41c00000, v206
	v_add_f32_e32 v13, 0x41c80000, v206
	v_cmp_le_f32_e64 vcc, |v12|, s91
	v_cmp_le_f32_e64 s[52:53], |v13|, s91
	v_fma_f32 v12, s46, -|v12|, v78
	v_fma_f32 v13, s46, -|v13|, v79
	v_cndmask_b32_e32 v12, v242, v12, vcc
	v_cndmask_b32_e64 v13, v242, v13, s[52:53]
	v_add_f32_e32 v14, 0x41d00000, v206
	v_add_f32_e32 v15, 0x41d80000, v206
	v_cmp_le_f32_e64 vcc, |v14|, s91
	v_cmp_le_f32_e64 s[52:53], |v15|, s91
	v_fma_f32 v14, s46, -|v14|, v80
	v_fma_f32 v15, s46, -|v15|, v81
	v_cndmask_b32_e32 v14, v242, v14, vcc
	v_cndmask_b32_e64 v15, v242, v15, s[52:53]
	v_add_f32_e32 v16, 0x42000000, v206
	v_add_f32_e32 v17, 0x42040000, v206
	v_cmp_le_f32_e64 vcc, |v16|, s91
	v_cmp_le_f32_e64 s[52:53], |v17|, s91
	v_fma_f32 v16, s46, -|v16|, v82
	v_fma_f32 v17, s46, -|v17|, v83
	v_cndmask_b32_e32 v16, v242, v16, vcc
	v_cndmask_b32_e64 v17, v242, v17, s[52:53]
	v_add_f32_e32 v18, 0x42080000, v206
	v_add_f32_e32 v19, 0x420c0000, v206
	v_cmp_le_f32_e64 vcc, |v18|, s91
	v_cmp_le_f32_e64 s[52:53], |v19|, s91
	v_fma_f32 v18, s46, -|v18|, v84
	v_fma_f32 v19, s46, -|v19|, v85
	v_cndmask_b32_e32 v18, v242, v18, vcc
	v_cndmask_b32_e64 v19, v242, v19, s[52:53]
	v_add_f32_e32 v20, 0x42200000, v206
	v_add_f32_e32 v21, 0x42240000, v206
	v_cmp_le_f32_e64 vcc, |v20|, s91
	v_cmp_le_f32_e64 s[52:53], |v21|, s91
	v_fma_f32 v20, s46, -|v20|, v86
	v_fma_f32 v21, s46, -|v21|, v87
	v_cndmask_b32_e32 v20, v242, v20, vcc
	v_cndmask_b32_e64 v21, v242, v21, s[52:53]
	v_add_f32_e32 v22, 0x42280000, v206
	v_add_f32_e32 v23, 0x422c0000, v206
	v_cmp_le_f32_e64 vcc, |v22|, s91
	v_cmp_le_f32_e64 s[52:53], |v23|, s91
	v_fma_f32 v22, s46, -|v22|, v88
	v_fma_f32 v23, s46, -|v23|, v89
	v_cndmask_b32_e32 v22, v242, v22, vcc
	v_cndmask_b32_e64 v23, v242, v23, s[52:53]
	v_add_f32_e32 v24, 0x42400000, v206
	v_add_f32_e32 v25, 0x42440000, v206
	v_cmp_le_f32_e64 vcc, |v24|, s91
	v_cmp_le_f32_e64 s[52:53], |v25|, s91
	v_fma_f32 v24, s46, -|v24|, v90
	v_fma_f32 v25, s46, -|v25|, v91
	v_cndmask_b32_e32 v24, v242, v24, vcc
	v_cndmask_b32_e64 v25, v242, v25, s[52:53]
	v_add_f32_e32 v26, 0x42480000, v206
	v_add_f32_e32 v27, 0x424c0000, v206
	v_cmp_le_f32_e64 vcc, |v26|, s91
	v_cmp_le_f32_e64 s[52:53], |v27|, s91
	v_fma_f32 v26, s46, -|v26|, v92
	v_fma_f32 v27, s46, -|v27|, v93
	v_cndmask_b32_e32 v26, v242, v26, vcc
	v_cndmask_b32_e64 v27, v242, v27, s[52:53]
	v_add_f32_e32 v28, 0x42600000, v206
	v_add_f32_e32 v29, 0x42640000, v206
	v_cmp_le_f32_e64 vcc, |v28|, s91
	v_cmp_le_f32_e64 s[52:53], |v29|, s91
	v_fma_f32 v28, s46, -|v28|, v94
	v_fma_f32 v29, s46, -|v29|, v95
	v_cndmask_b32_e32 v28, v242, v28, vcc
	v_cndmask_b32_e64 v29, v242, v29, s[52:53]
	v_add_f32_e32 v30, 0x42680000, v206
	v_add_f32_e32 v31, 0x426c0000, v206
	v_cmp_le_f32_e64 vcc, |v30|, s91
	v_cmp_le_f32_e64 s[52:53], |v31|, s91
	v_fma_f32 v30, s46, -|v30|, v96
	v_fma_f32 v31, s46, -|v31|, v97
	v_cndmask_b32_e32 v30, v242, v30, vcc
	v_cndmask_b32_e64 v31, v242, v31, s[52:53]
	s_mov_b64 s[52:53], 0
